# P0: waves 4-7 run the XN conversion before the weight transposes (streams overlap); K-loop MMA no-op trims; residual folding; tile order; sink s_load; transpose unroll
# speedup vs baseline: 1.0095x; 1.0031x over previous
; #define LAS __attribute__((address_space(3)))
; __device__ __forceinline__ void p0_prologue(const Params& p, LAS unsigned char* lds, int vcu_in, int G_in, int cu0, int part) {
;     const int tid = threadIdx.x, lane = tid & 63, wave = tid >> 6;
;     const int vcu = vcu_in - cu0, G = G_in - cu0;
;     if (vcu < 0) return;
;     const int gw = vcu * 8 + wave, NGW = G * 8;
;     unsigned char* ws = p.ws; unsigned char* dob = (unsigned char*)p.out;
;     {
;         LAS float* scr = (LAS float*)(lds + wave * 16384);
;         constexpr int I_IN = 32 * 176, I_OUT = 32 * 64, I_MKV = 32 * 32, I_L = I_IN + I_OUT;
;         if (part == 0) {
;             for (int it = gw; it < 2 * I_MKV; it += NGW) { const int l = it / I_MKV, r = it % I_MKV;
;                 transpose_item<false>(p.w_mem_kv + (size_t)l * 2048 * 1024, 2048, 1024, (bf16_t*)(dob + DO_WMKV) + (size_t)l * 1024 * 2048, scr, r, lane); }
;         } else
;         for (int it = gw; it < 2 * I_L; it += NGW) {
;             const int l = it / I_L; int r = it % I_L;
;             if (r < I_IN) { bf16_t* dst = l == 0 ? (bf16_t*)(dob + DO_WIN0) : (bf16_t*)(ws + WS_WIN1);
;                 transpose_item<true>(p.w_in + (size_t)l * 2048 * 5632, 2048, 5632, dst, scr, r, lane, l == 1 ? p.norm_in + 2048 : nullptr); continue; }
;             r -= I_IN;
;             { const int k0 = 64 * (r / 64);
;               const float* gk = k0 < 1024 ? p.g_attn + l * 1024 : (k0 < 1536 ? p.g_conv + l * 512 - 1024 : p.g_mem + l * 512 - 1536);
;               transpose_item<false>(p.w_out + (size_t)l * 2048 * 2048, 2048, 2048, (bf16_t*)(ws + WS_WOUT) + (size_t)l * 2048 * 2048, scr, r, lane, gk); }
.LBB0_93:
	s_andn2_b64 vcc, exec, s[0:1]
	s_cbranch_vccnz .LBB0_285
	s_sub_i32 s5, s2, 24
	s_sub_i32 s33, s70, 24
	v_lshl_add_u32 v66, s5, 3, v142
	s_movk_i32 s0, 0x3c00
	s_lshl_b32 s4, s33, 3
	v_cmp_gt_u32_e32 vcc, s0, v66
	v_and_b32_e32 v64, 31, v129
	s_and_b32 s100, s81, 0x100
	s_cbranch_scc1 .Lp0_xn_entry
.Lp0_tr_entry:
	s_and_saveexec_b64 s[6:7], vcc
	s_cbranch_execz .LBB0_273
	s_add_u32 s8, s68, 0x1c000000
	s_addc_u32 s9, s69, 0
	v_lshlrev_b32_e32 v1, 3, v129
	s_add_u32 s37, s68, 0x1d000000
	v_lshrrev_b32_e32 v17, 3, v128
	v_and_b32_e32 v18, 56, v1
	s_addc_u32 s38, s69, 0
	v_lshl_add_u32 v0, v142, 14, 0
	v_lshrrev_b32_e32 v12, 5, v128
	v_mul_u32_u24_e32 v1, 0x84, v18
	v_lshlrev_b32_e32 v2, 2, v17
	v_or_b32_e32 v26, 8, v17
	v_or_b32_e32 v27, 16, v17
	v_or_b32_e32 v28, 24, v17
	s_add_u32 s39, s60, 0x2000
	s_movk_i32 s12, 0xe800
	s_movk_i32 s14, 0xf000
	v_mov_b32_e32 v15, 0
	v_lshl_add_u32 v16, v64, 2, v0
	s_movk_i32 s36, 0x84
	v_add3_u32 v19, v0, v1, v2
	v_lshlrev_b32_e32 v29, 1, v17
	v_lshlrev_b32_e32 v30, 1, v26
	v_lshlrev_b32_e32 v31, 1, v27
	v_lshlrev_b32_e32 v32, 1, v28
	s_addc_u32 s40, s61, 0
	v_mov_b32_e32 v13, v12
	s_mov_b64 s[10:11], 0
	s_mov_b32 s41, 0x88888889
	s_movk_i32 s42, 0x15ff
	s_movk_i32 s43, 0x3ff
	s_movk_i32 s44, 0x5ff
	s_mov_b32 s13, -1
	s_mov_b32 s15, -1
	s_mov_b32 s45, 0x2c00000
	s_movk_i32 s46, 0x5800
	s_movk_i32 s47, 0xe1ff
	s_movk_i32 s48, 0xe200
	s_movk_i32 s49, 0x7c0
	s_movk_i32 s50, 0xffc0
	s_movk_i32 s51, 0x4ff
	s_movk_i32 s56, 0x9ff
	s_movk_i32 s57, 0xbff
	s_movk_i32 s58, 0xdff
	s_movk_i32 s59, 0xfff
	s_movk_i32 s72, 0x11ff
	s_movk_i32 s73, 0x13ff
	s_mov_b32 s74, 0x7fffff00
	s_movk_i32 s75, 0x3bff
	v_lshlrev_b32_e32 v20, 2, v64
	v_mov_b32_e32 v33, 6
	v_mov_b32_e32 v34, 0x7fffe400
	v_mov_b32_e32 v35, 0x7fffe800
	v_mov_b32_e32 v36, v66
	s_branch .LBB0_98

; __device__ __forceinline__ void p0_prologue(const Params& p, LAS unsigned char* lds, int vcu_in, int G_in, int cu0, int part) {
;     ...
;         for (int j = 0; j < 8; ++j) g[j] = ((const f32x4*)p.norm_in)[lane + 64 * j];
;         bf16_t* XN = (bf16_t*)(ws + WS_XN);
;         for (int row = gw; row < T_TOK; row += NGW) {
;             const float* xr = row < 16384 ? p.x_prompt + (size_t)row * 2048 : p.x_sample + (size_t)(row - 16384) * 2048;
;             f32x4 v[8]; float s = 0.f;
; #pragma unroll
;             for (int j = 0; j < 8; ++j) { v[j] = ((const f32x4*)xr)[lane + 64 * j]; s += (v[j][0] * v[j][0] + v[j][1] * v[j][1]) + (v[j][2] * v[j][2] + v[j][3] * v[j][3]); }
.LBB0_276:
	s_or_b64 exec, exec, s[0:1]
	s_cmp_lg_u32 s100, 0
	s_cbranch_scc1 .Lp0_after_xn
.Lp0_xn_entry:
	s_mov_b32 s0, 0x8000
	v_cmp_gt_i32_e32 vcc, s0, v66
	s_and_saveexec_b64 s[6:7], vcc
	s_cbranch_execz .LBB0_281
	v_lshlrev_b32_e32 v16, 4, v128
	global_load_dwordx4 v[0:3], v16, s[60:61]
	global_load_dwordx4 v[4:7], v16, s[60:61] offset:1024
	global_load_dwordx4 v[8:11], v16, s[60:61] offset:2048
	global_load_dwordx4 v[12:15], v16, s[60:61] offset:3072
	v_or_b32_e32 v32, 0x100, v128
	v_or_b32_e32 v34, 0x140, v128
	v_or_b32_e32 v36, 0x180, v128
	v_lshlrev_b32_e32 v24, 4, v32
	v_lshlrev_b32_e32 v25, 4, v34
	v_lshlrev_b32_e32 v33, 4, v36
	v_or_b32_e32 v38, 0x1c0, v128
	global_load_dwordx4 v[16:19], v24, s[60:61]
	global_load_dwordx4 v[20:23], v25, s[60:61]
	v_lshlrev_b32_e32 v35, 4, v38
	global_load_dwordx4 v[24:27], v33, s[60:61]
	global_load_dwordx4 v[28:31], v35, s[60:61]
	v_ashrrev_i32_e32 v67, 31, v66
	v_lshlrev_b32_e32 v33, 2, v128
	v_mov_b64_e32 v[40:41], 0x1ed00000
	s_ashr_i32 s5, s4, 31
	v_lshlrev_b64 v[74:75], 12, v[66:67]
	v_mov_b32_e32 v71, 0
	v_xor_b32_e32 v65, 4, v33
	v_xor_b32_e32 v84, 8, v33
	v_xor_b32_e32 v85, 16, v33
	v_xor_b32_e32 v86, 32, v33
	v_xor_b32_e32 v87, 64, v33
	v_xor_b32_e32 v88, 0x80, v33
	v_cmp_eq_u32_e64 s[0:1], 0, v128
	v_lshl_add_u64 v[72:73], v[66:67], 2, v[40:41]
	s_lshl_b64 s[8:9], s[4:5], 2
	v_lshl_or_b32 v74, v128, 3, v74
	s_lshl_b64 s[10:11], s[4:5], 12
	s_mov_b64 s[12:13], 0
	s_movk_i32 s16, 0x4000
	v_lshlrev_b32_e32 v70, 4, v128
	v_lshlrev_b32_e32 v76, 4, v32
	v_lshlrev_b32_e32 v78, 4, v34
	v_lshlrev_b32_e32 v80, 4, v36
	v_lshlrev_b32_e32 v82, 4, v38
	s_movk_i32 s17, 0x7fff
	s_branch .LBB0_279

; __device__ __forceinline__ void p0_prologue(const Params& p, LAS unsigned char* lds, int vcu_in, int G_in, int cu0, int part) {
;     ...
;     if (part == 1) {
;         f32x2* rope = (f32x2*)(ws + WS_ROPE);
;         for (int i = vcu * NTHREADS + tid; i < 16384 * 32; i += G * NTHREADS) {
;             const int pos = i >> 5, fi = i & 31;
;             const double rev = (double)pos * INVF_REV[fi];
;             const float fr = (float)(rev - __builtin_rint(rev));
;             f32x2 cs; cs[0] = __builtin_amdgcn_cosf(fr); cs[1] = __builtin_amdgcn_sinf(fr);
;             rope[i] = cs;
;         }
.LBB0_281:
	s_or_b64 exec, exec, s[6:7]
	s_cmp_eq_u32 s100, 0x100
	s_cbranch_scc0 .Lp0_after_xn
	s_mov_b32 s100, 1
	s_sub_i32 s5, s2, 24
	v_lshl_add_u32 v66, s5, 3, v142
	s_movk_i32 s0, 0x3c00
	v_cmp_gt_u32_e32 vcc, s0, v66
	s_nop 1
	s_branch .Lp0_tr_entry
.Lp0_after_xn:
	s_mov_b32 s0, 0x80000
	v_cmp_gt_i32_e32 vcc, s0, v68
	s_and_saveexec_b64 s[0:1], vcc
	s_cbranch_execz .LBB0_284
	v_lshlrev_b32_e32 v0, 3, v64
	s_getpc_b64 s[4:5]
	s_add_u32 s4, s4, _ZL8INVF_REV@rel32@lo+4
	s_addc_u32 s5, s5, _ZL8INVF_REV@rel32@hi+12
	global_load_dwordx2 v[0:1], v0, s[4:5]
	s_lshl_b32 s4, s33, 9
	v_lshl_add_u64 v[2:3], v[68:69], 3, s[68:69]
	s_mov_b64 s[6:7], 0x1e900000
	s_ashr_i32 s5, s4, 31
	v_lshl_add_u64 v[2:3], v[2:3], 0, s[6:7]
	s_lshl_b64 s[6:7], s[4:5], 3
	s_mov_b64 s[8:9], 0
	s_mov_b32 s5, 0x7ffff
	s_waitcnt vmcnt(0)

; #define PG8_STAGE(bufoff, gbase, voff) do { _Pragma("unroll") for (int _i = 0; _i < 2; ++_i) \
;         __builtin_amdgcn_global_load_lds((const unsigned*)((const char*)(gbase) + (voff)[_i]), (PG8_LAS unsigned*)(lds + (bufoff) + ldsw + _i * 8192), 16, 0, 0); } while (0)
; #define PG8_LDA(dst, b, h) do { _Pragma("unroll") for (int m = 0; m < 4; ++m) _Pragma("unroll") for (int k = 0; k < 2; ++k) dst[m][k] = *(const PG8_LAS bf16x8*)(lds + PG8_SA(b, h) + aoff + m * 2048 + k * 1024); } while (0)
; #define PG8_LDB(dst, b, h) do { _Pragma("unroll") for (int n = 0; n < 2; ++n) _Pragma("unroll") for (int k = 0; k < 2; ++k) dst[n][k] = *(const PG8_LAS bf16x8*)(lds + PG8_SB(b, h) + boff + n * 2048 + k * 1024); } while (0)
; #define PG8_MMA(ai, bj, At, Bt) do { __builtin_amdgcn_s_setprio(1); _Pragma("unroll") for (int m = 0; m < 4; ++m) _Pragma("unroll") for (int n = 0; n < 2; ++n) _Pragma("unroll") for (int k = 0; k < 2; ++k) \
;         acc[ai][bj][m][n] = __builtin_amdgcn_mfma_f32_16x16x32_bf16(Bt[n][k], At[m][k], acc[ai][bj][m][n], 0, 0, 0); __builtin_amdgcn_s_setprio(0); } while (0)
; #define PG8_WAIT_V(n) asm volatile("s_waitcnt vmcnt(" #n ")" ::: "memory")
; #define PG8_WAIT_L(n) asm volatile("s_waitcnt lgkmcnt(" #n ")" ::: "memory")
; #define PG8_BAR __builtin_amdgcn_s_barrier()
; #define PG8_SCHED __builtin_amdgcn_sched_barrier(0)
; template <class Epi, class Sched, bool ALIGN_EPI = false, bool SP2 = true>
; __device__ __forceinline__ void gemm_phase(PG8_LAS unsigned char* lds, const Gemm g, const Sched& S, const Epi& E, int wave_s) {
;     ...
;             PG8_LDB(B0, 0, 0); PG8_LDB(B1, 0, 1); PG8_SCHED; PG8_LDA(At, 0, 0); PG8_STAGE(PG8_SA(1, 1), a1 + hstepA, voffA);
;             PG8_WAIT_V(8); PG8_WAIT_L(0); PG8_BAR; PG8_MMA(0, 0, At, B0); PG8_MMA(0, 1, At, B1); PG8_BAR; PG8_SCHED;
.LBB0_345:
	s_add_u32 s6, s4, 0xfff80080
	s_addc_u32 s7, s5, -1
	s_add_i32 s73, 0, 0x10000
	s_cmp_eq_u32 s72, 28
	s_cselect_b32 s11, s23, s7
	s_cselect_b32 s10, s28, s6
	v_add_u32_e32 v144, s73, v139
	s_cselect_b32 s7, s21, s46
	s_cselect_b32 s6, s29, s33
	s_add_i32 s76, 0, 0x14000
	ds_read_b128 v[154:157], v144
	ds_read_b128 v[158:161], v144 offset:1024
	ds_read_b128 v[162:165], v144 offset:2048
	ds_read_b128 v[166:169], v144 offset:3072
	v_add_u32_e32 v144, s76, v139
	ds_read_b128 v[176:179], v144
	ds_read_b128 v[180:183], v144 offset:1024
	ds_read_b128 v[184:187], v144 offset:2048
	ds_read_b128 v[188:191], v144 offset:3072
	v_lshl_add_u64 v[144:145], s[4:5], 0, v[142:143]
	s_add_i32 m0, s35, 0xc000
	ds_read_b128 v[192:195], v174
	ds_read_b128 v[196:199], v174 offset:1024
	ds_read_b128 v[200:203], v174 offset:2048
	ds_read_b128 v[204:207], v174 offset:3072
	ds_read_b128 v[208:211], v174 offset:4096
	ds_read_b128 v[212:215], v174 offset:5120
	ds_read_b128 v[216:219], v174 offset:6144
	ds_read_b128 v[220:223], v174 offset:7168
	global_load_lds_dwordx4 v[144:145], off
	v_lshl_add_u64 v[144:145], s[4:5], 0, v[140:141]
	s_add_i32 m0, s35, 0xe000
	s_nop 0
	global_load_lds_dwordx4 v[144:145], off
	s_waitcnt vmcnt(8)
	s_waitcnt lgkmcnt(0)
	s_barrier
	s_setprio 1
	v_mfma_f32_16x16x32_bf16 v[126:129], v[154:157], v[192:195], v[126:129]
	v_mfma_f32_16x16x32_bf16 v[122:125], v[162:165], v[192:195], v[122:125]
	v_mfma_f32_16x16x32_bf16 v[110:113], v[154:157], v[200:203], v[110:113]
	v_mfma_f32_16x16x32_bf16 v[106:109], v[162:165], v[200:203], v[106:109]
	v_mfma_f32_16x16x32_bf16 v[94:97], v[154:157], v[208:211], v[94:97]
	v_mfma_f32_16x16x32_bf16 v[90:93], v[162:165], v[208:211], v[90:93]
	v_mfma_f32_16x16x32_bf16 v[78:81], v[154:157], v[216:219], v[78:81]
	v_mfma_f32_16x16x32_bf16 v[74:77], v[162:165], v[216:219], v[74:77]
	v_mfma_f32_16x16x32_bf16 v[126:129], v[158:161], v[196:199], v[126:129]
	v_mfma_f32_16x16x32_bf16 v[122:125], v[166:169], v[196:199], v[122:125]
	v_mfma_f32_16x16x32_bf16 v[110:113], v[158:161], v[204:207], v[110:113]
	v_mfma_f32_16x16x32_bf16 v[106:109], v[166:169], v[204:207], v[106:109]
	v_mfma_f32_16x16x32_bf16 v[94:97], v[158:161], v[212:215], v[94:97]
	v_mfma_f32_16x16x32_bf16 v[90:93], v[166:169], v[212:215], v[90:93]
	v_mfma_f32_16x16x32_bf16 v[78:81], v[158:161], v[220:223], v[78:81]
	v_mfma_f32_16x16x32_bf16 v[74:77], v[166:169], v[220:223], v[74:77]
	v_mfma_f32_16x16x32_bf16 v[118:121], v[176:179], v[192:195], v[118:121]
	v_mfma_f32_16x16x32_bf16 v[114:117], v[184:187], v[192:195], v[114:117]
	v_mfma_f32_16x16x32_bf16 v[102:105], v[176:179], v[200:203], v[102:105]
	v_mfma_f32_16x16x32_bf16 v[98:101], v[184:187], v[200:203], v[98:101]
	v_mfma_f32_16x16x32_bf16 v[86:89], v[176:179], v[208:211], v[86:89]
	v_mfma_f32_16x16x32_bf16 v[82:85], v[184:187], v[208:211], v[82:85]
	v_mfma_f32_16x16x32_bf16 v[70:73], v[176:179], v[216:219], v[70:73]
	v_mfma_f32_16x16x32_bf16 v[66:69], v[184:187], v[216:219], v[66:69]
	v_mfma_f32_16x16x32_bf16 v[118:121], v[180:183], v[196:199], v[118:121]
	v_mfma_f32_16x16x32_bf16 v[114:117], v[188:191], v[196:199], v[114:117]
	v_mfma_f32_16x16x32_bf16 v[102:105], v[180:183], v[204:207], v[102:105]
	v_mfma_f32_16x16x32_bf16 v[98:101], v[188:191], v[204:207], v[98:101]
	v_mfma_f32_16x16x32_bf16 v[86:89], v[180:183], v[212:215], v[86:89]
	v_mfma_f32_16x16x32_bf16 v[82:85], v[188:191], v[212:215], v[82:85]
	v_mfma_f32_16x16x32_bf16 v[70:73], v[180:183], v[220:223], v[70:73]
	v_mfma_f32_16x16x32_bf16 v[66:69], v[188:191], v[220:223], v[66:69]
	s_setprio 0
	s_barrier
	s_add_i32 s73, s73, s34
	v_lshl_add_u64 v[144:145], s[6:7], 0, v[134:135]
	s_mov_b32 m0, s73
	ds_read_b128 v[192:195], v174 offset:16384
	ds_read_b128 v[196:199], v174 offset:17408
	ds_read_b128 v[200:203], v174 offset:18432
	ds_read_b128 v[204:207], v174 offset:19456
	ds_read_b128 v[208:211], v174 offset:20480
	ds_read_b128 v[212:215], v174 offset:21504
	ds_read_b128 v[216:219], v174 offset:22528
	ds_read_b128 v[220:223], v174 offset:23552
	global_load_lds_dwordx4 v[144:145], off
	s_add_i32 m0, s73, 0x2000
	s_add_u32 s74, s6, 0x80000
	v_lshl_add_u64 v[170:171], s[6:7], 0, v[130:131]
	s_addc_u32 s75, s7, 0
	s_add_i32 s73, s76, s34
	global_load_lds_dwordx4 v[170:171], off
	v_lshl_add_u64 v[224:225], s[74:75], 0, v[134:135]
	s_mov_b32 m0, s73
	v_lshl_add_u64 v[226:227], s[10:11], 0, v[132:133]
	global_load_lds_dwordx4 v[224:225], off
	v_lshl_add_u64 v[224:225], s[74:75], 0, v[130:131]
	s_add_i32 m0, s73, 0x2000
	s_nop 0
	global_load_lds_dwordx4 v[224:225], off
	v_lshl_add_u64 v[224:225], s[10:11], 0, v[136:137]
	s_mov_b32 m0, s35
	s_nop 0
	global_load_lds_dwordx4 v[224:225], off
	s_mov_b32 m0, s37
	s_nop 0
	global_load_lds_dwordx4 v[226:227], off
	s_waitcnt vmcnt(8)
	s_waitcnt lgkmcnt(0)
	s_barrier
; #define PG8_STAGE(bufoff, gbase, voff) do { _Pragma("unroll") for (int _i = 0; _i < 2; ++_i) \
;         __builtin_amdgcn_global_load_lds((const unsigned*)((const char*)(gbase) + (voff)[_i]), (PG8_LAS unsigned*)(lds + (bufoff) + ldsw + _i * 8192), 16, 0, 0); } while (0)
; #define PG8_LDA(dst, b, h) do { _Pragma("unroll") for (int m = 0; m < 4; ++m) _Pragma("unroll") for (int k = 0; k < 2; ++k) dst[m][k] = *(const PG8_LAS bf16x8*)(lds + PG8_SA(b, h) + aoff + m * 2048 + k * 1024); } while (0)
; #define PG8_LDB(dst, b, h) do { _Pragma("unroll") for (int n = 0; n < 2; ++n) _Pragma("unroll") for (int k = 0; k < 2; ++k) dst[n][k] = *(const PG8_LAS bf16x8*)(lds + PG8_SB(b, h) + boff + n * 2048 + k * 1024); } while (0)
; #define PG8_MMA(ai, bj, At, Bt) do { __builtin_amdgcn_s_setprio(1); _Pragma("unroll") for (int m = 0; m < 4; ++m) _Pragma("unroll") for (int n = 0; n < 2; ++n) _Pragma("unroll") for (int k = 0; k < 2; ++k) \
;         acc[ai][bj][m][n] = __builtin_amdgcn_mfma_f32_16x16x32_bf16(Bt[n][k], At[m][k], acc[ai][bj][m][n], 0, 0, 0); __builtin_amdgcn_s_setprio(0); } while (0)
; #define PG8_WAIT_V(n) asm volatile("s_waitcnt vmcnt(" #n ")" ::: "memory")
; #define PG8_WAIT_L(n) asm volatile("s_waitcnt lgkmcnt(" #n ")" ::: "memory")
; #define PG8_BAR __builtin_amdgcn_s_barrier()
; #define PG8_SCHED __builtin_amdgcn_sched_barrier(0)
; template <class Epi, class Sched, bool ALIGN_EPI = false, bool SP2 = true>
; __device__ __forceinline__ void gemm_phase(PG8_LAS unsigned char* lds, const Gemm g, const Sched& S, const Epi& E, int wave_s) {
;     ...
;             PG8_LDA(At, 0, 1); PG8_STAGE(PG8_SB(0, 0), b2, voffB); PG8_STAGE(PG8_SB(0, 1), b2 + hstepB, voffB); PG8_STAGE(PG8_SA(0, 0), a2, voffA);
;             PG8_WAIT_V(8); PG8_WAIT_L(0); PG8_BAR; PG8_MMA(1, 0, At, B0); PG8_MMA(1, 1, At, B1); PG8_BAR; PG8_SCHED;
;             PG8_LDB(B0, 1, 0); PG8_LDB(B1, 1, 1); PG8_SCHED; PG8_LDA(At, 1, 0); PG8_STAGE(PG8_SA(0, 1), a2 + hstepA, voffA);
;             PG8_WAIT_V(8); PG8_WAIT_L(0); PG8_BAR; PG8_MMA(0, 0, At, B0); PG8_MMA(0, 1, At, B1); PG8_BAR; PG8_SCHED;
	s_setprio 1
	v_mfma_f32_16x16x32_bf16 v[62:65], v[154:157], v[192:195], v[62:65]
	v_mfma_f32_16x16x32_bf16 v[58:61], v[162:165], v[192:195], v[58:61]
	v_mfma_f32_16x16x32_bf16 v[46:49], v[154:157], v[200:203], v[46:49]
	v_mfma_f32_16x16x32_bf16 v[42:45], v[162:165], v[200:203], v[42:45]
	v_mfma_f32_16x16x32_bf16 v[30:33], v[154:157], v[208:211], v[30:33]
	v_mfma_f32_16x16x32_bf16 v[26:29], v[162:165], v[208:211], v[26:29]
	v_mfma_f32_16x16x32_bf16 v[14:17], v[154:157], v[216:219], v[14:17]
	v_mfma_f32_16x16x32_bf16 v[10:13], v[162:165], v[216:219], v[10:13]
	v_mfma_f32_16x16x32_bf16 v[62:65], v[158:161], v[196:199], v[62:65]
	v_mfma_f32_16x16x32_bf16 v[58:61], v[166:169], v[196:199], v[58:61]
	v_mfma_f32_16x16x32_bf16 v[46:49], v[158:161], v[204:207], v[46:49]
	v_mfma_f32_16x16x32_bf16 v[42:45], v[166:169], v[204:207], v[42:45]
	v_mfma_f32_16x16x32_bf16 v[30:33], v[158:161], v[212:215], v[30:33]
	v_mfma_f32_16x16x32_bf16 v[26:29], v[166:169], v[212:215], v[26:29]
	v_mfma_f32_16x16x32_bf16 v[14:17], v[158:161], v[220:223], v[14:17]
	v_mfma_f32_16x16x32_bf16 v[10:13], v[166:169], v[220:223], v[10:13]
	v_mfma_f32_16x16x32_bf16 v[54:57], v[176:179], v[192:195], v[54:57]
	v_mfma_f32_16x16x32_bf16 v[50:53], v[184:187], v[192:195], v[50:53]
	v_mfma_f32_16x16x32_bf16 v[38:41], v[176:179], v[200:203], v[38:41]
	v_mfma_f32_16x16x32_bf16 v[34:37], v[184:187], v[200:203], v[34:37]
	v_mfma_f32_16x16x32_bf16 v[22:25], v[176:179], v[208:211], v[22:25]
	v_mfma_f32_16x16x32_bf16 v[18:21], v[184:187], v[208:211], v[18:21]
	v_mfma_f32_16x16x32_bf16 v[6:9], v[176:179], v[216:219], v[6:9]
	v_mfma_f32_16x16x32_bf16 v[2:5], v[184:187], v[216:219], v[2:5]
	v_mfma_f32_16x16x32_bf16 v[54:57], v[180:183], v[196:199], v[54:57]
	v_mfma_f32_16x16x32_bf16 v[50:53], v[188:191], v[196:199], v[50:53]
	v_mfma_f32_16x16x32_bf16 v[38:41], v[180:183], v[204:207], v[38:41]
	v_mfma_f32_16x16x32_bf16 v[34:37], v[188:191], v[204:207], v[34:37]
	v_mfma_f32_16x16x32_bf16 v[22:25], v[180:183], v[212:215], v[22:25]
	v_mfma_f32_16x16x32_bf16 v[18:21], v[188:191], v[212:215], v[18:21]
	v_mfma_f32_16x16x32_bf16 v[6:9], v[180:183], v[220:223], v[6:9]
	v_mfma_f32_16x16x32_bf16 v[2:5], v[188:191], v[220:223], v[2:5]
	s_setprio 0
	s_barrier
	s_add_i32 s73, 0, 0x18000
	v_add_u32_e32 v146, s73, v139
	s_add_i32 s74, 0, 0x1c000
	ds_read_b128 v[154:157], v146
	ds_read_b128 v[158:161], v146 offset:1024
	ds_read_b128 v[162:165], v146 offset:2048
	ds_read_b128 v[166:169], v146 offset:3072
	v_add_u32_e32 v146, s74, v139
	ds_read_b128 v[176:179], v146
	ds_read_b128 v[180:183], v146 offset:1024
	ds_read_b128 v[184:187], v146 offset:2048
	ds_read_b128 v[188:191], v146 offset:3072
	s_add_u32 s10, s10, 0x80000
	s_addc_u32 s11, s11, 0
	s_mov_b32 m0, s38
	v_lshl_add_u64 v[228:229], s[10:11], 0, v[136:137]
	ds_read_b128 v[192:195], v174 offset:32768
	ds_read_b128 v[196:199], v174 offset:33792
	ds_read_b128 v[200:203], v174 offset:34816
	ds_read_b128 v[204:207], v174 offset:35840
	ds_read_b128 v[208:211], v174 offset:36864
	ds_read_b128 v[212:215], v174 offset:37888
	ds_read_b128 v[216:219], v174 offset:38912
	ds_read_b128 v[220:223], v174 offset:39936
	global_load_lds_dwordx4 v[228:229], off
	v_lshl_add_u64 v[228:229], s[10:11], 0, v[132:133]
	s_mov_b32 m0, s39
	s_nop 0
	global_load_lds_dwordx4 v[228:229], off
	s_waitcnt vmcnt(8)
	s_waitcnt lgkmcnt(0)
	s_barrier
	s_setprio 1
	v_mfma_f32_16x16x32_bf16 v[126:129], v[154:157], v[192:195], v[126:129]
	v_mfma_f32_16x16x32_bf16 v[122:125], v[162:165], v[192:195], v[122:125]
	v_mfma_f32_16x16x32_bf16 v[110:113], v[154:157], v[200:203], v[110:113]
	v_mfma_f32_16x16x32_bf16 v[106:109], v[162:165], v[200:203], v[106:109]
	v_mfma_f32_16x16x32_bf16 v[94:97], v[154:157], v[208:211], v[94:97]
	v_mfma_f32_16x16x32_bf16 v[90:93], v[162:165], v[208:211], v[90:93]
	v_mfma_f32_16x16x32_bf16 v[78:81], v[154:157], v[216:219], v[78:81]
	v_mfma_f32_16x16x32_bf16 v[74:77], v[162:165], v[216:219], v[74:77]
	v_mfma_f32_16x16x32_bf16 v[126:129], v[158:161], v[196:199], v[126:129]
	v_mfma_f32_16x16x32_bf16 v[122:125], v[166:169], v[196:199], v[122:125]
	v_mfma_f32_16x16x32_bf16 v[110:113], v[158:161], v[204:207], v[110:113]
	v_mfma_f32_16x16x32_bf16 v[106:109], v[166:169], v[204:207], v[106:109]
	v_mfma_f32_16x16x32_bf16 v[94:97], v[158:161], v[212:215], v[94:97]
	v_mfma_f32_16x16x32_bf16 v[90:93], v[166:169], v[212:215], v[90:93]
	v_mfma_f32_16x16x32_bf16 v[78:81], v[158:161], v[220:223], v[78:81]
	v_mfma_f32_16x16x32_bf16 v[74:77], v[166:169], v[220:223], v[74:77]
	v_mfma_f32_16x16x32_bf16 v[118:121], v[176:179], v[192:195], v[118:121]
	v_mfma_f32_16x16x32_bf16 v[114:117], v[184:187], v[192:195], v[114:117]
	v_mfma_f32_16x16x32_bf16 v[102:105], v[176:179], v[200:203], v[102:105]
	v_mfma_f32_16x16x32_bf16 v[98:101], v[184:187], v[200:203], v[98:101]
	v_mfma_f32_16x16x32_bf16 v[86:89], v[176:179], v[208:211], v[86:89]
	v_mfma_f32_16x16x32_bf16 v[82:85], v[184:187], v[208:211], v[82:85]
	v_mfma_f32_16x16x32_bf16 v[70:73], v[176:179], v[216:219], v[70:73]
	v_mfma_f32_16x16x32_bf16 v[66:69], v[184:187], v[216:219], v[66:69]
	v_mfma_f32_16x16x32_bf16 v[118:121], v[180:183], v[196:199], v[118:121]
	v_mfma_f32_16x16x32_bf16 v[114:117], v[188:191], v[196:199], v[114:117]
	v_mfma_f32_16x16x32_bf16 v[102:105], v[180:183], v[204:207], v[102:105]
	v_mfma_f32_16x16x32_bf16 v[98:101], v[188:191], v[204:207], v[98:101]
	v_mfma_f32_16x16x32_bf16 v[86:89], v[180:183], v[212:215], v[86:89]
	v_mfma_f32_16x16x32_bf16 v[82:85], v[188:191], v[212:215], v[82:85]
	v_mfma_f32_16x16x32_bf16 v[70:73], v[180:183], v[220:223], v[70:73]
	v_mfma_f32_16x16x32_bf16 v[66:69], v[188:191], v[220:223], v[66:69]
	s_setprio 0
	s_barrier
; #define PG8_STAGE(bufoff, gbase, voff) do { _Pragma("unroll") for (int _i = 0; _i < 2; ++_i) \
;         __builtin_amdgcn_global_load_lds((const unsigned*)((const char*)(gbase) + (voff)[_i]), (PG8_LAS unsigned*)(lds + (bufoff) + ldsw + _i * 8192), 16, 0, 0); } while (0)
; #define PG8_LDA(dst, b, h) do { _Pragma("unroll") for (int m = 0; m < 4; ++m) _Pragma("unroll") for (int k = 0; k < 2; ++k) dst[m][k] = *(const PG8_LAS bf16x8*)(lds + PG8_SA(b, h) + aoff + m * 2048 + k * 1024); } while (0)
; #define PG8_MMA(ai, bj, At, Bt) do { __builtin_amdgcn_s_setprio(1); _Pragma("unroll") for (int m = 0; m < 4; ++m) _Pragma("unroll") for (int n = 0; n < 2; ++n) _Pragma("unroll") for (int k = 0; k < 2; ++k) \
;         acc[ai][bj][m][n] = __builtin_amdgcn_mfma_f32_16x16x32_bf16(Bt[n][k], At[m][k], acc[ai][bj][m][n], 0, 0, 0); __builtin_amdgcn_s_setprio(0); } while (0)
; #define PG8_WAIT_V(n) asm volatile("s_waitcnt vmcnt(" #n ")" ::: "memory")
; #define PG8_WAIT_L(n) asm volatile("s_waitcnt lgkmcnt(" #n ")" ::: "memory")
; #define PG8_BAR __builtin_amdgcn_s_barrier()
; #define PG8_SCHED __builtin_amdgcn_sched_barrier(0)
; template <class Epi, class Sched, bool ALIGN_EPI = false, bool SP2 = true>
; __device__ __forceinline__ void gemm_phase(PG8_LAS unsigned char* lds, const Gemm g, const Sched& S, const Epi& E, int wave_s) {
;     ...
;             PG8_LDA(At, 1, 1); PG8_STAGE(PG8_SB(1, 0), b3, voffB); PG8_STAGE(PG8_SB(1, 1), b3 + hstepB, voffB); PG8_STAGE(PG8_SA(1, 0), a3, voffA);
;             PG8_WAIT_V(8); PG8_WAIT_L(0); PG8_BAR; PG8_MMA(1, 0, At, B0); PG8_MMA(1, 1, At, B1); PG8_BAR; PG8_SCHED;
	s_add_i32 s10, s73, s34
	v_lshl_add_u64 v[144:145], v[144:145], 0, s[78:79]
	s_mov_b32 m0, s10
	ds_read_b128 v[192:195], v174 offset:49152
	ds_read_b128 v[196:199], v174 offset:50176
	ds_read_b128 v[200:203], v174 offset:51200
	ds_read_b128 v[204:207], v174 offset:52224
	ds_read_b128 v[208:211], v174 offset:53248
	ds_read_b128 v[212:215], v174 offset:54272
	ds_read_b128 v[216:219], v174 offset:55296
	ds_read_b128 v[220:223], v174 offset:56320
	global_load_lds_dwordx4 v[144:145], off
	s_add_i32 m0, s10, 0x2000
	s_add_u32 s6, s6, 0x80080
	v_lshl_add_u64 v[144:145], v[170:171], 0, s[78:79]
	s_addc_u32 s7, s7, 0
	s_add_i32 s10, s74, s34
	global_load_lds_dwordx4 v[144:145], off
	v_lshl_add_u64 v[144:145], s[6:7], 0, v[134:135]
	s_mov_b32 m0, s10
	s_nop 0
	global_load_lds_dwordx4 v[144:145], off
	v_lshl_add_u64 v[144:145], s[6:7], 0, v[130:131]
	s_add_i32 m0, s10, 0x2000
	s_nop 0
	global_load_lds_dwordx4 v[144:145], off
	v_lshl_add_u64 v[144:145], v[224:225], 0, s[78:79]
	s_mov_b32 m0, s44
	s_nop 0
	global_load_lds_dwordx4 v[144:145], off
	v_lshl_add_u64 v[144:145], v[226:227], 0, s[78:79]
	s_mov_b32 m0, s45
	s_nop 0
	global_load_lds_dwordx4 v[144:145], off
	s_waitcnt vmcnt(8)
	s_waitcnt lgkmcnt(0)
	s_barrier
	s_setprio 1
	v_mfma_f32_16x16x32_bf16 v[62:65], v[154:157], v[192:195], v[62:65]
	v_mfma_f32_16x16x32_bf16 v[58:61], v[162:165], v[192:195], v[58:61]
	v_mfma_f32_16x16x32_bf16 v[46:49], v[154:157], v[200:203], v[46:49]
	v_mfma_f32_16x16x32_bf16 v[42:45], v[162:165], v[200:203], v[42:45]
	v_mfma_f32_16x16x32_bf16 v[30:33], v[154:157], v[208:211], v[30:33]
	v_mfma_f32_16x16x32_bf16 v[26:29], v[162:165], v[208:211], v[26:29]
	v_mfma_f32_16x16x32_bf16 v[14:17], v[154:157], v[216:219], v[14:17]
	v_mfma_f32_16x16x32_bf16 v[10:13], v[162:165], v[216:219], v[10:13]
	v_mfma_f32_16x16x32_bf16 v[62:65], v[158:161], v[196:199], v[62:65]
	v_mfma_f32_16x16x32_bf16 v[58:61], v[166:169], v[196:199], v[58:61]
	v_mfma_f32_16x16x32_bf16 v[46:49], v[158:161], v[204:207], v[46:49]
	v_mfma_f32_16x16x32_bf16 v[42:45], v[166:169], v[204:207], v[42:45]
	v_mfma_f32_16x16x32_bf16 v[30:33], v[158:161], v[212:215], v[30:33]
	v_mfma_f32_16x16x32_bf16 v[26:29], v[166:169], v[212:215], v[26:29]
	v_mfma_f32_16x16x32_bf16 v[14:17], v[158:161], v[220:223], v[14:17]
	v_mfma_f32_16x16x32_bf16 v[10:13], v[166:169], v[220:223], v[10:13]
	v_mfma_f32_16x16x32_bf16 v[54:57], v[176:179], v[192:195], v[54:57]
	v_mfma_f32_16x16x32_bf16 v[50:53], v[184:187], v[192:195], v[50:53]
	v_mfma_f32_16x16x32_bf16 v[38:41], v[176:179], v[200:203], v[38:41]
	v_mfma_f32_16x16x32_bf16 v[34:37], v[184:187], v[200:203], v[34:37]
	v_mfma_f32_16x16x32_bf16 v[22:25], v[176:179], v[208:211], v[22:25]
	v_mfma_f32_16x16x32_bf16 v[18:21], v[184:187], v[208:211], v[18:21]
	v_mfma_f32_16x16x32_bf16 v[6:9], v[176:179], v[216:219], v[6:9]
	v_mfma_f32_16x16x32_bf16 v[2:5], v[184:187], v[216:219], v[2:5]
	v_mfma_f32_16x16x32_bf16 v[54:57], v[180:183], v[196:199], v[54:57]
	v_mfma_f32_16x16x32_bf16 v[50:53], v[188:191], v[196:199], v[50:53]
	v_mfma_f32_16x16x32_bf16 v[38:41], v[180:183], v[204:207], v[38:41]
	v_mfma_f32_16x16x32_bf16 v[34:37], v[188:191], v[204:207], v[34:37]
	v_mfma_f32_16x16x32_bf16 v[22:25], v[180:183], v[212:215], v[22:25]
	v_mfma_f32_16x16x32_bf16 v[18:21], v[188:191], v[212:215], v[18:21]
	v_mfma_f32_16x16x32_bf16 v[6:9], v[180:183], v[220:223], v[6:9]
	v_mfma_f32_16x16x32_bf16 v[2:5], v[188:191], v[220:223], v[2:5]
	s_setprio 0
	s_barrier
	s_add_i32 s72, s72, 2
	s_add_u32 s33, s33, 0x100
	s_addc_u32 s46, s46, 0
	s_add_u32 s4, s4, 0x100
	s_addc_u32 s5, s5, 0
	s_cmp_gt_u32 s72, 29
	s_cbranch_scc0 .LBB0_345
	s_and_b64 vcc, exec, s[18:19]
	s_cbranch_vccz .LBB0_348
	s_barrier

; #define PG8_STAGE(bufoff, gbase, voff) do { _Pragma("unroll") for (int _i = 0; _i < 2; ++_i) \
;         __builtin_amdgcn_global_load_lds((const unsigned*)((const char*)(gbase) + (voff)[_i]), (PG8_LAS unsigned*)(lds + (bufoff) + ldsw + _i * 8192), 16, 0, 0); } while (0)
; #define PG8_LDA(dst, b, h) do { _Pragma("unroll") for (int m = 0; m < 4; ++m) _Pragma("unroll") for (int k = 0; k < 2; ++k) dst[m][k] = *(const PG8_LAS bf16x8*)(lds + PG8_SA(b, h) + aoff + m * 2048 + k * 1024); } while (0)
; #define PG8_LDB(dst, b, h) do { _Pragma("unroll") for (int n = 0; n < 2; ++n) _Pragma("unroll") for (int k = 0; k < 2; ++k) dst[n][k] = *(const PG8_LAS bf16x8*)(lds + PG8_SB(b, h) + boff + n * 2048 + k * 1024); } while (0)
; #define PG8_MMA(ai, bj, At, Bt) do { __builtin_amdgcn_s_setprio(1); _Pragma("unroll") for (int m = 0; m < 4; ++m) _Pragma("unroll") for (int n = 0; n < 2; ++n) _Pragma("unroll") for (int k = 0; k < 2; ++k) \
;         acc[ai][bj][m][n] = __builtin_amdgcn_mfma_f32_16x16x32_bf16(Bt[n][k], At[m][k], acc[ai][bj][m][n], 0, 0, 0); __builtin_amdgcn_s_setprio(0); } while (0)
; #define PG8_WAIT_V(n) asm volatile("s_waitcnt vmcnt(" #n ")" ::: "memory")
; #define PG8_WAIT_L(n) asm volatile("s_waitcnt lgkmcnt(" #n ")" ::: "memory")
; #define PG8_BAR __builtin_amdgcn_s_barrier()
; #define PG8_SCHED __builtin_amdgcn_sched_barrier(0)
; template <class Epi, class Sched, bool ALIGN_EPI = false, bool SP2 = true>
; __device__ __forceinline__ void gemm_phase(PG8_LAS unsigned char* lds, const Gemm g, const Sched& S, const Epi& E, int wave_s) {
;     ...
;             PG8_LDB(B0, 0, 0); PG8_LDB(B1, 0, 1); PG8_SCHED; PG8_LDA(At, 0, 0); PG8_STAGE(PG8_SA(1, 1), a1 + hstepA, voffA);
;             PG8_WAIT_V(8); PG8_WAIT_L(0); PG8_BAR; PG8_MMA(0, 0, At, B0); PG8_MMA(0, 1, At, B1); PG8_BAR; PG8_SCHED;
;             PG8_LDA(At, 0, 1); PG8_STAGE(PG8_SB(0, 0), b2, voffB); PG8_STAGE(PG8_SB(0, 1), b2 + hstepB, voffB); PG8_STAGE(PG8_SA(0, 0), a2, voffA);
.LBB0_608:
	s_add_u32 s6, s24, 0x100
	s_addc_u32 s7, s25, 0
	s_add_i32 s75, 0, 0x10000
	s_cmp_eq_u32 s74, 28
	s_cselect_b32 s29, s21, s7
	s_cselect_b32 s28, s20, s6
	v_add_u32_e32 v146, s75, v170
	s_cselect_b32 s27, s19, s73
	s_cselect_b32 s26, s33, s72
	s_add_i32 s76, 0, 0x14000
	ds_read_b128 v[130:133], v146
	ds_read_b128 v[134:137], v146 offset:1024
	ds_read_b128 v[158:161], v146 offset:2048
	ds_read_b128 v[162:165], v146 offset:3072
	v_add_u32_e32 v146, s76, v170
	ds_read_b128 v[166:169], v146
	ds_read_b128 v[176:179], v146 offset:1024
	ds_read_b128 v[180:183], v146 offset:2048
	ds_read_b128 v[184:187], v146 offset:3072
	v_lshl_add_u64 v[146:147], s[24:25], 0, v[156:157]
	s_add_i32 m0, s35, 0xc000
	ds_read_b128 v[188:191], v174
	ds_read_b128 v[192:195], v174 offset:1024
	ds_read_b128 v[196:199], v174 offset:2048
	ds_read_b128 v[200:203], v174 offset:3072
	ds_read_b128 v[204:207], v174 offset:4096
	ds_read_b128 v[208:211], v174 offset:5120
	ds_read_b128 v[212:215], v174 offset:6144
	ds_read_b128 v[216:219], v174 offset:7168
	global_load_lds_dwordx4 v[146:147], off
	v_lshl_add_u64 v[146:147], s[24:25], 0, v[154:155]
	s_add_i32 m0, s35, 0xe000
	s_nop 0
	global_load_lds_dwordx4 v[146:147], off
	s_waitcnt vmcnt(8)
	s_waitcnt lgkmcnt(0)
	s_barrier
	s_setprio 1
	v_mfma_f32_16x16x32_bf16 v[126:129], v[130:133], v[188:191], v[126:129]
	v_mfma_f32_16x16x32_bf16 v[122:125], v[158:161], v[188:191], v[122:125]
	v_mfma_f32_16x16x32_bf16 v[110:113], v[130:133], v[196:199], v[110:113]
	v_mfma_f32_16x16x32_bf16 v[106:109], v[158:161], v[196:199], v[106:109]
	v_mfma_f32_16x16x32_bf16 v[94:97], v[130:133], v[204:207], v[94:97]
	v_mfma_f32_16x16x32_bf16 v[90:93], v[158:161], v[204:207], v[90:93]
	v_mfma_f32_16x16x32_bf16 v[78:81], v[130:133], v[212:215], v[78:81]
	v_mfma_f32_16x16x32_bf16 v[74:77], v[158:161], v[212:215], v[74:77]
	v_mfma_f32_16x16x32_bf16 v[126:129], v[134:137], v[192:195], v[126:129]
	v_mfma_f32_16x16x32_bf16 v[122:125], v[162:165], v[192:195], v[122:125]
	v_mfma_f32_16x16x32_bf16 v[110:113], v[134:137], v[200:203], v[110:113]
	v_mfma_f32_16x16x32_bf16 v[106:109], v[162:165], v[200:203], v[106:109]
	v_mfma_f32_16x16x32_bf16 v[94:97], v[134:137], v[208:211], v[94:97]
	v_mfma_f32_16x16x32_bf16 v[90:93], v[162:165], v[208:211], v[90:93]
	v_mfma_f32_16x16x32_bf16 v[78:81], v[134:137], v[216:219], v[78:81]
	v_mfma_f32_16x16x32_bf16 v[74:77], v[162:165], v[216:219], v[74:77]
	v_mfma_f32_16x16x32_bf16 v[118:121], v[166:169], v[188:191], v[118:121]
	v_mfma_f32_16x16x32_bf16 v[114:117], v[180:183], v[188:191], v[114:117]
	v_mfma_f32_16x16x32_bf16 v[102:105], v[166:169], v[196:199], v[102:105]
	v_mfma_f32_16x16x32_bf16 v[98:101], v[180:183], v[196:199], v[98:101]
	v_mfma_f32_16x16x32_bf16 v[86:89], v[166:169], v[204:207], v[86:89]
	v_mfma_f32_16x16x32_bf16 v[82:85], v[180:183], v[204:207], v[82:85]
	v_mfma_f32_16x16x32_bf16 v[70:73], v[166:169], v[212:215], v[70:73]
	v_mfma_f32_16x16x32_bf16 v[66:69], v[180:183], v[212:215], v[66:69]
	v_mfma_f32_16x16x32_bf16 v[118:121], v[176:179], v[192:195], v[118:121]
	v_mfma_f32_16x16x32_bf16 v[114:117], v[184:187], v[192:195], v[114:117]
	v_mfma_f32_16x16x32_bf16 v[102:105], v[176:179], v[200:203], v[102:105]
	v_mfma_f32_16x16x32_bf16 v[98:101], v[184:187], v[200:203], v[98:101]
	v_mfma_f32_16x16x32_bf16 v[86:89], v[176:179], v[208:211], v[86:89]
	v_mfma_f32_16x16x32_bf16 v[82:85], v[184:187], v[208:211], v[82:85]
	v_mfma_f32_16x16x32_bf16 v[70:73], v[176:179], v[216:219], v[70:73]
	v_mfma_f32_16x16x32_bf16 v[66:69], v[184:187], v[216:219], v[66:69]
	s_setprio 0
	s_barrier
	s_add_i32 s24, s75, s34
	v_lshl_add_u64 v[146:147], s[26:27], 0, v[142:143]
	s_mov_b32 m0, s24
	ds_read_b128 v[188:191], v174 offset:16384
	ds_read_b128 v[192:195], v174 offset:17408
	ds_read_b128 v[196:199], v174 offset:18432
	ds_read_b128 v[200:203], v174 offset:19456
	ds_read_b128 v[204:207], v174 offset:20480
	ds_read_b128 v[208:211], v174 offset:21504
	ds_read_b128 v[212:215], v174 offset:22528
	ds_read_b128 v[216:219], v174 offset:23552
	global_load_lds_dwordx4 v[146:147], off
	s_add_i32 m0, s24, 0x2000
	s_add_u32 s24, s26, 0x80000
	v_lshl_add_u64 v[220:221], s[26:27], 0, v[138:139]
	s_addc_u32 s25, s27, 0
	s_add_i32 s75, s76, s34
	global_load_lds_dwordx4 v[220:221], off
	v_lshl_add_u64 v[222:223], s[24:25], 0, v[142:143]
	s_mov_b32 m0, s75
	v_lshl_add_u64 v[224:225], s[28:29], 0, v[140:141]
	global_load_lds_dwordx4 v[222:223], off
	v_lshl_add_u64 v[222:223], s[24:25], 0, v[138:139]
	s_add_i32 m0, s75, 0x2000
	s_nop 0
	global_load_lds_dwordx4 v[222:223], off
	v_lshl_add_u64 v[222:223], s[28:29], 0, v[144:145]
	s_mov_b32 m0, s35
	s_nop 0
	global_load_lds_dwordx4 v[222:223], off
	s_mov_b32 m0, s37
	s_nop 0
	global_load_lds_dwordx4 v[224:225], off
	s_cmp_lt_i32 s74, 0
	s_cbranch_scc1 .Lrf_join
	s_cmp_eq_u32 s92, 0
	s_cbranch_scc1 .Lrf_tree
	v_lshlrev_b32_e32 v240, 16, v228
	v_and_b32_e32 v241, 0xffff0000, v228
	v_lshlrev_b32_e32 v242, 16, v229
	v_and_b32_e32 v243, 0xffff0000, v229
	v_lshlrev_b32_e32 v244, 16, v230
	v_and_b32_e32 v245, 0xffff0000, v230
	v_lshlrev_b32_e32 v246, 16, v231
	v_and_b32_e32 v247, 0xffff0000, v231

; #define GAS __attribute__((address_space(1)))
; __device__ __forceinline__ float bf_lo(unsigned w) { return __uint_as_float(w << 16); }
; __device__ __forceinline__ float bf_hi(unsigned w) { return __uint_as_float(w & 0xffff0000u); }
; #define PG8_MMA(ai, bj, At, Bt) do { __builtin_amdgcn_s_setprio(1); _Pragma("unroll") for (int m = 0; m < 4; ++m) _Pragma("unroll") for (int n = 0; n < 2; ++n) _Pragma("unroll") for (int k = 0; k < 2; ++k) \
;         acc[ai][bj][m][n] = __builtin_amdgcn_mfma_f32_16x16x32_bf16(Bt[n][k], At[m][k], acc[ai][bj][m][n], 0, 0, 0); __builtin_amdgcn_s_setprio(0); } while (0)
; #define PG8_WAIT_V(n) asm volatile("s_waitcnt vmcnt(" #n ")" ::: "memory")
; #define PG8_WAIT_L(n) asm volatile("s_waitcnt lgkmcnt(" #n ")" ::: "memory")
; #define PG8_BAR __builtin_amdgcn_s_barrier()
; #define PG8_SCHED __builtin_amdgcn_sched_barrier(0)
;     __device__ __forceinline__ void operator()(const f32x4 (&acc)[2][2][4][2], const Unit& u, int wr, int wc, int fr, int fq, const PG8_LAS float* tab) const {
;     ...
;                     if (mode == 0) { a0 = *(const GAS f32x4*)(xo + col0); a1 = *(const GAS f32x4*)(xo + col0 + 4); }
;                     else { const u32x4 w = *(const GAS u32x4*)(xr + col0);
;                         a0 = (f32x4){bf_lo(w.x), bf_hi(w.x), bf_lo(w.y), bf_hi(w.y)}; a1 = (f32x4){bf_lo(w.z), bf_hi(w.z), bf_lo(w.w), bf_hi(w.w)}; }
;                     const f32x4 v0 = a0 + acc[ai][bj][m][0] * ra, v1 = a1 + acc[ai][bj][m][1] * ra;
; template <class Epi, class Sched, bool ALIGN_EPI = false, bool SP2 = true>
; __device__ __forceinline__ void gemm_phase(PG8_LAS unsigned char* lds, const Gemm g, const Sched& S, const Epi& E, int wave_s) {
;     ...
;             PG8_WAIT_V(8); PG8_WAIT_L(0); PG8_BAR; PG8_MMA(1, 0, At, B0); PG8_MMA(1, 1, At, B1); PG8_BAR; PG8_SCHED;
.Lrf_join:
	s_waitcnt vmcnt(8)
	s_waitcnt lgkmcnt(0)
	s_barrier
	s_setprio 1
	v_mfma_f32_16x16x32_bf16 v[62:65], v[130:133], v[188:191], v[62:65]
	v_mfma_f32_16x16x32_bf16 v[58:61], v[158:161], v[188:191], v[58:61]
	v_mfma_f32_16x16x32_bf16 v[46:49], v[130:133], v[196:199], v[46:49]
	v_mfma_f32_16x16x32_bf16 v[42:45], v[158:161], v[196:199], v[42:45]
	v_mfma_f32_16x16x32_bf16 v[30:33], v[130:133], v[204:207], v[30:33]
	v_mfma_f32_16x16x32_bf16 v[26:29], v[158:161], v[204:207], v[26:29]
	v_mfma_f32_16x16x32_bf16 v[14:17], v[130:133], v[212:215], v[14:17]
	v_mfma_f32_16x16x32_bf16 v[10:13], v[158:161], v[212:215], v[10:13]
	v_mfma_f32_16x16x32_bf16 v[62:65], v[134:137], v[192:195], v[62:65]
	v_mfma_f32_16x16x32_bf16 v[58:61], v[162:165], v[192:195], v[58:61]
	v_mfma_f32_16x16x32_bf16 v[46:49], v[134:137], v[200:203], v[46:49]
	v_mfma_f32_16x16x32_bf16 v[42:45], v[162:165], v[200:203], v[42:45]
	v_mfma_f32_16x16x32_bf16 v[30:33], v[134:137], v[208:211], v[30:33]
	v_mfma_f32_16x16x32_bf16 v[26:29], v[162:165], v[208:211], v[26:29]
	v_mfma_f32_16x16x32_bf16 v[14:17], v[134:137], v[216:219], v[14:17]
	v_mfma_f32_16x16x32_bf16 v[10:13], v[162:165], v[216:219], v[10:13]
	v_mfma_f32_16x16x32_bf16 v[54:57], v[166:169], v[188:191], v[54:57]
	v_mfma_f32_16x16x32_bf16 v[50:53], v[180:183], v[188:191], v[50:53]
	v_mfma_f32_16x16x32_bf16 v[38:41], v[166:169], v[196:199], v[38:41]
	v_mfma_f32_16x16x32_bf16 v[34:37], v[180:183], v[196:199], v[34:37]
	v_mfma_f32_16x16x32_bf16 v[22:25], v[166:169], v[204:207], v[22:25]
	v_mfma_f32_16x16x32_bf16 v[18:21], v[180:183], v[204:207], v[18:21]
	v_mfma_f32_16x16x32_bf16 v[6:9], v[166:169], v[212:215], v[6:9]
	v_mfma_f32_16x16x32_bf16 v[2:5], v[180:183], v[212:215], v[2:5]
	v_mfma_f32_16x16x32_bf16 v[54:57], v[176:179], v[192:195], v[54:57]
	v_mfma_f32_16x16x32_bf16 v[50:53], v[184:187], v[192:195], v[50:53]
	v_mfma_f32_16x16x32_bf16 v[38:41], v[176:179], v[200:203], v[38:41]
	v_mfma_f32_16x16x32_bf16 v[34:37], v[184:187], v[200:203], v[34:37]
	v_mfma_f32_16x16x32_bf16 v[22:25], v[176:179], v[208:211], v[22:25]
	v_mfma_f32_16x16x32_bf16 v[18:21], v[184:187], v[208:211], v[18:21]
	v_mfma_f32_16x16x32_bf16 v[6:9], v[176:179], v[216:219], v[6:9]
	v_mfma_f32_16x16x32_bf16 v[2:5], v[184:187], v[216:219], v[2:5]
	s_setprio 0
	s_barrier
	s_add_i32 s77, s74, 2
	s_lshr_b32 s32, s77, 4
	s_lshl_b32 s32, s32, 20
	s_bfe_u32 s100, s77, 0x20002
	s_lshl_b32 s100, s100, 17
	s_or_b32 s32, s32, s100
	s_and_b32 s100, s77, 2
	s_lshl_b32 s100, s100, 8
	s_or_b32 s32, s32, s100
	s_and_b32 s100, s92, 1
	s_lshr_b32 s32, s32, s100
	s_add_u32 s100, s94, s32
	s_addc_u32 s101, s95, 0
	s_cmp_eq_u32 s92, 0
	s_cbranch_scc0 .Lrf_ld_m1
	global_load_dwordx4 v[240:243], v250, s[100:101]
	global_load_dwordx4 v[244:247], v250, s[100:101] offset:16
	s_branch .Lrf_ld_done

; #define PG8_STAGE(bufoff, gbase, voff) do { _Pragma("unroll") for (int _i = 0; _i < 2; ++_i) \
;         __builtin_amdgcn_global_load_lds((const unsigned*)((const char*)(gbase) + (voff)[_i]), (PG8_LAS unsigned*)(lds + (bufoff) + ldsw + _i * 8192), 16, 0, 0); } while (0)
; #define PG8_LDA(dst, b, h) do { _Pragma("unroll") for (int m = 0; m < 4; ++m) _Pragma("unroll") for (int k = 0; k < 2; ++k) dst[m][k] = *(const PG8_LAS bf16x8*)(lds + PG8_SA(b, h) + aoff + m * 2048 + k * 1024); } while (0)
; #define PG8_LDB(dst, b, h) do { _Pragma("unroll") for (int n = 0; n < 2; ++n) _Pragma("unroll") for (int k = 0; k < 2; ++k) dst[n][k] = *(const PG8_LAS bf16x8*)(lds + PG8_SB(b, h) + boff + n * 2048 + k * 1024); } while (0)
; #define PG8_MMA(ai, bj, At, Bt) do { __builtin_amdgcn_s_setprio(1); _Pragma("unroll") for (int m = 0; m < 4; ++m) _Pragma("unroll") for (int n = 0; n < 2; ++n) _Pragma("unroll") for (int k = 0; k < 2; ++k) \
;         acc[ai][bj][m][n] = __builtin_amdgcn_mfma_f32_16x16x32_bf16(Bt[n][k], At[m][k], acc[ai][bj][m][n], 0, 0, 0); __builtin_amdgcn_s_setprio(0); } while (0)
; #define PG8_WAIT_V(n) asm volatile("s_waitcnt vmcnt(" #n ")" ::: "memory")
; #define PG8_WAIT_L(n) asm volatile("s_waitcnt lgkmcnt(" #n ")" ::: "memory")
; #define PG8_BAR __builtin_amdgcn_s_barrier()
; #define PG8_SCHED __builtin_amdgcn_sched_barrier(0)
; template <class Epi, class Sched, bool ALIGN_EPI = false, bool SP2 = true>
; __device__ __forceinline__ void gemm_phase(PG8_LAS unsigned char* lds, const Gemm g, const Sched& S, const Epi& E, int wave_s) {
;     ...
;             PG8_LDB(B0, 1, 0); PG8_LDB(B1, 1, 1); PG8_SCHED; PG8_LDA(At, 1, 0); PG8_STAGE(PG8_SA(0, 1), a2 + hstepA, voffA);
;             PG8_WAIT_V(8); PG8_WAIT_L(0); PG8_BAR; PG8_MMA(0, 0, At, B0); PG8_MMA(0, 1, At, B1); PG8_BAR; PG8_SCHED;
.Lrf_ld_done:
	s_add_i32 s75, 0, 0x18000
	s_add_i32 s76, 0, 0x1c000
	v_add_u32_e32 v162, s75, v170
	v_add_u32_e32 v175, s76, v170
	ds_read_b128 v[130:133], v162
	ds_read_b128 v[134:137], v162 offset:1024
	ds_read_b128 v[158:161], v162 offset:2048
	ds_read_b128 v[162:165], v162 offset:3072
	ds_read_b128 v[166:169], v175
	ds_read_b128 v[176:179], v175 offset:1024
	ds_read_b128 v[180:183], v175 offset:2048
	ds_read_b128 v[184:187], v175 offset:3072
	s_add_u32 s24, s28, 0x140000
	s_addc_u32 s25, s29, 0
	s_mov_b32 m0, s42
	v_lshl_add_u64 v[226:227], s[24:25], 0, v[144:145]
	ds_read_b128 v[188:191], v174 offset:32768
	ds_read_b128 v[192:195], v174 offset:33792
	ds_read_b128 v[196:199], v174 offset:34816
	ds_read_b128 v[200:203], v174 offset:35840
	ds_read_b128 v[204:207], v174 offset:36864
	ds_read_b128 v[208:211], v174 offset:37888
	ds_read_b128 v[212:215], v174 offset:38912
	ds_read_b128 v[216:219], v174 offset:39936
	global_load_lds_dwordx4 v[226:227], off
	v_lshl_add_u64 v[226:227], s[24:25], 0, v[140:141]
	s_mov_b32 m0, s43
	s_nop 0
	global_load_lds_dwordx4 v[226:227], off
	s_waitcnt vmcnt(10)
	s_waitcnt lgkmcnt(0)
	s_barrier
	s_setprio 1
	v_mfma_f32_16x16x32_bf16 v[126:129], v[130:133], v[188:191], v[126:129]
	v_mfma_f32_16x16x32_bf16 v[122:125], v[158:161], v[188:191], v[122:125]
	v_mfma_f32_16x16x32_bf16 v[110:113], v[130:133], v[196:199], v[110:113]
	v_mfma_f32_16x16x32_bf16 v[106:109], v[158:161], v[196:199], v[106:109]
	v_mfma_f32_16x16x32_bf16 v[94:97], v[130:133], v[204:207], v[94:97]
	v_mfma_f32_16x16x32_bf16 v[90:93], v[158:161], v[204:207], v[90:93]
	v_mfma_f32_16x16x32_bf16 v[78:81], v[130:133], v[212:215], v[78:81]
	v_mfma_f32_16x16x32_bf16 v[74:77], v[158:161], v[212:215], v[74:77]
	v_mfma_f32_16x16x32_bf16 v[126:129], v[134:137], v[192:195], v[126:129]
	v_mfma_f32_16x16x32_bf16 v[122:125], v[162:165], v[192:195], v[122:125]
	v_mfma_f32_16x16x32_bf16 v[110:113], v[134:137], v[200:203], v[110:113]
	v_mfma_f32_16x16x32_bf16 v[106:109], v[162:165], v[200:203], v[106:109]
	v_mfma_f32_16x16x32_bf16 v[94:97], v[134:137], v[208:211], v[94:97]
	v_mfma_f32_16x16x32_bf16 v[90:93], v[162:165], v[208:211], v[90:93]
	v_mfma_f32_16x16x32_bf16 v[78:81], v[134:137], v[216:219], v[78:81]
	v_mfma_f32_16x16x32_bf16 v[74:77], v[162:165], v[216:219], v[74:77]
	v_mfma_f32_16x16x32_bf16 v[118:121], v[166:169], v[188:191], v[118:121]
	v_mfma_f32_16x16x32_bf16 v[114:117], v[180:183], v[188:191], v[114:117]
	v_mfma_f32_16x16x32_bf16 v[102:105], v[166:169], v[196:199], v[102:105]
	v_mfma_f32_16x16x32_bf16 v[98:101], v[180:183], v[196:199], v[98:101]
	v_mfma_f32_16x16x32_bf16 v[86:89], v[166:169], v[204:207], v[86:89]
	v_mfma_f32_16x16x32_bf16 v[82:85], v[180:183], v[204:207], v[82:85]
	v_mfma_f32_16x16x32_bf16 v[70:73], v[166:169], v[212:215], v[70:73]
	v_mfma_f32_16x16x32_bf16 v[66:69], v[180:183], v[212:215], v[66:69]
	v_mfma_f32_16x16x32_bf16 v[118:121], v[176:179], v[192:195], v[118:121]
	v_mfma_f32_16x16x32_bf16 v[114:117], v[184:187], v[192:195], v[114:117]
	v_mfma_f32_16x16x32_bf16 v[102:105], v[176:179], v[200:203], v[102:105]
	v_mfma_f32_16x16x32_bf16 v[98:101], v[184:187], v[200:203], v[98:101]
	v_mfma_f32_16x16x32_bf16 v[86:89], v[176:179], v[208:211], v[86:89]
	v_mfma_f32_16x16x32_bf16 v[82:85], v[184:187], v[208:211], v[82:85]
	v_mfma_f32_16x16x32_bf16 v[70:73], v[176:179], v[216:219], v[70:73]
	v_mfma_f32_16x16x32_bf16 v[66:69], v[184:187], v[216:219], v[66:69]
	s_setprio 0
	s_barrier
; #define PG8_STAGE(bufoff, gbase, voff) do { _Pragma("unroll") for (int _i = 0; _i < 2; ++_i) \
;         __builtin_amdgcn_global_load_lds((const unsigned*)((const char*)(gbase) + (voff)[_i]), (PG8_LAS unsigned*)(lds + (bufoff) + ldsw + _i * 8192), 16, 0, 0); } while (0)
; #define PG8_LDA(dst, b, h) do { _Pragma("unroll") for (int m = 0; m < 4; ++m) _Pragma("unroll") for (int k = 0; k < 2; ++k) dst[m][k] = *(const PG8_LAS bf16x8*)(lds + PG8_SA(b, h) + aoff + m * 2048 + k * 1024); } while (0)
; #define PG8_MMA(ai, bj, At, Bt) do { __builtin_amdgcn_s_setprio(1); _Pragma("unroll") for (int m = 0; m < 4; ++m) _Pragma("unroll") for (int n = 0; n < 2; ++n) _Pragma("unroll") for (int k = 0; k < 2; ++k) \
;         acc[ai][bj][m][n] = __builtin_amdgcn_mfma_f32_16x16x32_bf16(Bt[n][k], At[m][k], acc[ai][bj][m][n], 0, 0, 0); __builtin_amdgcn_s_setprio(0); } while (0)
; #define PG8_WAIT_V(n) asm volatile("s_waitcnt vmcnt(" #n ")" ::: "memory")
; #define PG8_WAIT_L(n) asm volatile("s_waitcnt lgkmcnt(" #n ")" ::: "memory")
; #define PG8_BAR __builtin_amdgcn_s_barrier()
; #define PG8_SCHED __builtin_amdgcn_sched_barrier(0)
; template <class Epi, class Sched, bool ALIGN_EPI = false, bool SP2 = true>
; __device__ __forceinline__ void gemm_phase(PG8_LAS unsigned char* lds, const Gemm g, const Sched& S, const Epi& E, int wave_s) {
;     ...
;             PG8_LDA(At, 1, 1); PG8_STAGE(PG8_SB(1, 0), b3, voffB); PG8_STAGE(PG8_SB(1, 1), b3 + hstepB, voffB); PG8_STAGE(PG8_SA(1, 0), a3, voffA);
;             PG8_WAIT_V(8); PG8_WAIT_L(0); PG8_BAR; PG8_MMA(1, 0, At, B0); PG8_MMA(1, 1, At, B1); PG8_BAR; PG8_SCHED;
	s_add_i32 s77, s74, 2
	s_lshr_b32 s77, s77, 2
	s_and_b32 s32, s77, 3
	s_lshl_b32 s32, s32, 6
	s_lshr_b32 s77, s77, 2
	s_lshl_b32 s77, s77, 9
	s_or_b32 s77, s77, s32
	v_add_u32_e32 v253, s77, v252
	ds_read_b32 v251, v253
	s_add_i32 s24, s75, s34
	v_lshl_add_u64 v[146:147], v[146:147], 0, s[78:79]
	s_mov_b32 m0, s24
	ds_read_b128 v[188:191], v174 offset:49152
	ds_read_b128 v[192:195], v174 offset:50176
	ds_read_b128 v[196:199], v174 offset:51200
	ds_read_b128 v[200:203], v174 offset:52224
	ds_read_b128 v[204:207], v174 offset:53248
	ds_read_b128 v[208:211], v174 offset:54272
	ds_read_b128 v[212:215], v174 offset:55296
	ds_read_b128 v[216:219], v174 offset:56320
	global_load_lds_dwordx4 v[146:147], off
	s_add_i32 m0, s24, 0x2000
	s_add_u32 s24, s26, 0x80080
	v_lshl_add_u64 v[146:147], v[220:221], 0, s[78:79]
	s_addc_u32 s25, s27, 0
	s_add_i32 s26, s76, s34
	global_load_lds_dwordx4 v[146:147], off
	v_lshl_add_u64 v[146:147], s[24:25], 0, v[142:143]
	s_mov_b32 m0, s26
	s_nop 0
	global_load_lds_dwordx4 v[146:147], off
	v_lshl_add_u64 v[146:147], s[24:25], 0, v[138:139]
	s_add_i32 m0, s26, 0x2000
	s_nop 0
	global_load_lds_dwordx4 v[146:147], off
	v_lshl_add_u64 v[146:147], v[222:223], 0, s[78:79]
	s_mov_b32 m0, s40
	s_nop 0
	global_load_lds_dwordx4 v[146:147], off
	v_lshl_add_u64 v[146:147], v[224:225], 0, s[78:79]
	s_mov_b32 m0, s41
	s_nop 0
	global_load_lds_dwordx4 v[146:147], off
	s_waitcnt vmcnt(10)
	s_waitcnt lgkmcnt(0)
	v_rcp_f32_e32 v248, v251
	s_barrier
	s_setprio 1
	v_mfma_f32_16x16x32_bf16 v[62:65], v[130:133], v[188:191], v[62:65]
	v_mfma_f32_16x16x32_bf16 v[58:61], v[158:161], v[188:191], v[58:61]
	v_mfma_f32_16x16x32_bf16 v[46:49], v[130:133], v[196:199], v[46:49]
	v_mfma_f32_16x16x32_bf16 v[42:45], v[158:161], v[196:199], v[42:45]
	v_mfma_f32_16x16x32_bf16 v[30:33], v[130:133], v[204:207], v[30:33]
	v_mfma_f32_16x16x32_bf16 v[26:29], v[158:161], v[204:207], v[26:29]
	v_mfma_f32_16x16x32_bf16 v[14:17], v[130:133], v[212:215], v[14:17]
	v_mfma_f32_16x16x32_bf16 v[10:13], v[158:161], v[212:215], v[10:13]
	v_mfma_f32_16x16x32_bf16 v[62:65], v[134:137], v[192:195], v[62:65]
	v_mfma_f32_16x16x32_bf16 v[58:61], v[162:165], v[192:195], v[58:61]
	v_mfma_f32_16x16x32_bf16 v[46:49], v[134:137], v[200:203], v[46:49]
	v_mfma_f32_16x16x32_bf16 v[42:45], v[162:165], v[200:203], v[42:45]
	v_mfma_f32_16x16x32_bf16 v[30:33], v[134:137], v[208:211], v[30:33]
	v_mfma_f32_16x16x32_bf16 v[26:29], v[162:165], v[208:211], v[26:29]
	v_mfma_f32_16x16x32_bf16 v[14:17], v[134:137], v[216:219], v[14:17]
	v_mfma_f32_16x16x32_bf16 v[10:13], v[162:165], v[216:219], v[10:13]
	v_mfma_f32_16x16x32_bf16 v[54:57], v[166:169], v[188:191], v[54:57]
	v_mfma_f32_16x16x32_bf16 v[50:53], v[180:183], v[188:191], v[50:53]
	v_mfma_f32_16x16x32_bf16 v[38:41], v[166:169], v[196:199], v[38:41]
	v_mfma_f32_16x16x32_bf16 v[34:37], v[180:183], v[196:199], v[34:37]
	v_mfma_f32_16x16x32_bf16 v[22:25], v[166:169], v[204:207], v[22:25]
	v_mfma_f32_16x16x32_bf16 v[18:21], v[180:183], v[204:207], v[18:21]
	v_mfma_f32_16x16x32_bf16 v[6:9], v[166:169], v[212:215], v[6:9]
	v_mfma_f32_16x16x32_bf16 v[2:5], v[180:183], v[212:215], v[2:5]
	v_mfma_f32_16x16x32_bf16 v[54:57], v[176:179], v[192:195], v[54:57]
	v_mfma_f32_16x16x32_bf16 v[50:53], v[184:187], v[192:195], v[50:53]
	v_mfma_f32_16x16x32_bf16 v[38:41], v[176:179], v[200:203], v[38:41]
	v_mfma_f32_16x16x32_bf16 v[34:37], v[184:187], v[200:203], v[34:37]
	v_mfma_f32_16x16x32_bf16 v[22:25], v[176:179], v[208:211], v[22:25]
	v_mfma_f32_16x16x32_bf16 v[18:21], v[184:187], v[208:211], v[18:21]
	v_mfma_f32_16x16x32_bf16 v[6:9], v[176:179], v[216:219], v[6:9]
	v_mfma_f32_16x16x32_bf16 v[2:5], v[184:187], v[216:219], v[2:5]
	s_setprio 0
	s_barrier
	s_add_i32 s74, s74, 2
	s_add_u32 s72, s72, 0x100
	s_addc_u32 s73, s73, 0
	s_cmp_gt_u32 s74, 29
	s_mov_b64 s[24:25], s[6:7]
	s_cbranch_scc0 .LBB0_608
	s_and_b64 vcc, exec, s[16:17]
	s_cbranch_vccz .LBB0_611
	s_barrier
